# mLSTM chain state-image publish staged through double-buffered LDS so each wave stores 1 KiB contiguous full lines (on top of deferred publish + p7 pull queue)
# speedup vs baseline: 1.0035x; 1.0031x over previous
.LBB0_1212:
	s_or_b64 exec, exec, s[12:13]
	v_mov_b32_e32 v86, 0x3f803f80
	s_add_i32 s12, s34, s30
	v_cndmask_b32_e64 v86, 0, v86, s[14:15]
	s_add_i32 s14, s12, s31
	s_lshl_b32 s12, s14, 6
	s_ashr_i32 s13, s12, 31
	s_lshl_b64 s[12:13], s[12:13], 2
	s_ashr_i32 s15, s14, 31
	s_mul_i32 s24, s14, 0x204000
	v_add_u32_e32 v101, 0, v91
	s_mul_hi_i32 s20, s14, 0x204000
	s_add_u32 s24, s22, s24
	v_add_u32_e32 v91, s35, v97
	s_addc_u32 s25, s23, s20
	v_add_lshl_u32 v114, v91, v98, 8
	v_mov_b32_e32 v115, 0
	v_mov_b32_e32 v91, 0x204000
	v_lshl_add_u64 v[102:103], s[24:25], 0, v[92:93]
	v_mad_i64_i32 v[92:93], s[24:25], s14, v91, v[114:115]
	v_lshrrev_b32_e32 v91, 1, v90
	v_and_or_b32 v92, v91, 16, v92
	s_lshl_b64 s[14:15], s[14:15], 20
	v_lshl_add_u64 v[104:105], v[92:93], 0, s[22:23]
	v_lshl_add_u64 v[92:93], s[14:15], 0, v[94:95]
	v_and_or_b32 v90, v90, 48, s14
	s_lshl_b32 s14, s21, 6
	v_mov_b32_e32 v97, v115
	s_and_b32 s14, s14, 0xfffffc00
	s_waitcnt lgkmcnt(0)
	s_barrier
	v_lshl_add_u64 v[106:107], v[92:93], 0, v[96:97]
	v_lshl_or_b32 v92, v98, 6, s14
	v_lshl_add_u32 v100, v88, 4, 0
	v_mul_u32_u24_e32 v110, 0x90, v98
	v_mov_b32_e32 v91, s15
	v_ashrrev_i32_e32 v93, 31, v92
	v_mov_b32_e32 v87, v86
	v_mov_b32_e32 v88, v86
	v_mov_b32_e32 v89, v86
	v_lshl_add_u64 v[108:109], v[92:93], 1, v[90:91]
	s_add_i32 s28, 0, 0x9400
	s_mov_b32 s29, -8
	v_mov_b32_e32 v130, 0xf210000
	s_mov_b64 s[14:15], 0x40800
	s_mov_b64 s[20:21], 0x20000
	v_add_u32_e32 v131, v101, v99
	v_add_u32_e32 v133, v100, v110
	v_mov_b32_e32 v120, v115
	v_mov_b32_e32 v121, v115
	v_mov_b32_e32 v116, v115
	v_mov_b32_e32 v117, v115
	v_mov_b32_e32 v126, v115
	v_mov_b32_e32 v127, v115
	v_mov_b32_e32 v124, v115
	v_mov_b32_e32 v125, v115
	v_mov_b32_e32 v118, v115
	v_mov_b32_e32 v119, v115
	v_mov_b32_e32 v122, v115
	v_mov_b32_e32 v123, v115
	v_and_b32_e32 v240, 63, v0
	v_lshrrev_b32_e32 v241, 6, v0
	v_and_b32_e32 v242, 15, v240
	v_lshrrev_b32_e32 v243, 4, v240
	v_and_b32_e32 v244, 1, v243
	v_lshl_add_u32 v244, v244, 4, v242
	v_lshrrev_b32_e32 v245, 1, v243
	v_mul_u32_u24_e32 v247, 0x110, v244
	v_lshl_add_u32 v247, v241, 5, v247
	v_lshl_add_u32 v247, v245, 4, v247
	v_add_u32_e32 v247, 0xa000, v247
	v_lshl_add_u32 v250, v241, 2, v243
	v_mul_u32_u24_e32 v246, 0x110, v250
	v_lshl_add_u32 v246, v242, 4, v246
	v_add_u32_e32 v246, 0xa000, v246
	v_sub_u32_e32 v248, v250, v244
	v_lshlrev_b32_e32 v248, 8, v248
	v_sub_u32_e32 v249, v242, v245
	v_lshl_add_u32 v248, v249, 4, v248
	v_lshlrev_b32_e32 v249, 5, v241
	v_sub_u32_e32 v248, v248, v249
	v_ashrrev_i32_e32 v249, 31, v248
	s_branch .LBB0_1215

.LBB0_1219:
	s_or_b64 exec, exec, s[22:23]
	v_mov_b32_e32 v110, s28
	ds_read_b128 v[134:137], v133
	ds_read_b64 v[110:111], v110
	ds_read_b128 v[138:141], v133 offset:64
	ds_read_b128 v[146:149], v133 offset:2304
	s_waitcnt vmcnt(16) lgkmcnt(3)
	v_mfma_f32_16x16x32_bf16 v[142:145], v[2:5], v[134:137], 0
	s_waitcnt lgkmcnt(2)
	v_add_f32_e32 v110, v115, v110
	v_max_f32_e32 v111, v111, v111
	v_max_f32_e32 v134, v110, v111
	v_sub_f32_e32 v110, v110, v134
	v_mul_f32_e32 v110, 0x3fb8aa3b, v110
	v_exp_f32_e32 v110, v110
	v_mul_f32_e32 v111, 0xbfb8aa3b, v134
	s_waitcnt vmcnt(15) lgkmcnt(1)
	v_mfma_f32_16x16x32_bf16 v[136:139], v[6:9], v[138:141], v[142:145]
	v_mul_f32_e64 v114, v126, v110
	v_mul_f32_e64 v115, v127, v110
	v_pk_mul_f32 v[124:125], v[124:125], v[110:111] op_sel_hi:[1,0]
	ds_read_b128 v[140:143], v133 offset:2368
	s_waitcnt lgkmcnt(1)
	v_mfma_f32_16x16x32_bf16 v[144:147], v[2:5], v[146:149], 0
	v_exp_f32_e32 v148, v111
	s_nop 0
	v_pk_fma_f32 v[124:125], v[138:139], v[148:149], v[124:125] op_sel_hi:[1,0,1]
	v_pk_fma_f32 v[128:129], v[136:137], v[148:149], v[114:115] op_sel_hi:[1,0,1]
	v_mfma_f32_16x16x32_bf16 v[136:139], v[2:5], v[86:89], 0
	s_waitcnt lgkmcnt(0)
	v_mfma_f32_16x16x32_bf16 v[140:143], v[6:9], v[140:143], v[144:147]
	v_mfma_f32_16x16x32_bf16 v[136:139], v[6:9], v[86:89], v[136:139]
	s_nop 6
	v_mul_f32_e64 v114, v148, v142
	v_mul_f32_e64 v115, v148, v143
	v_pk_mul_f32 v[126:127], v[148:149], v[140:141] op_sel_hi:[0,1]
	v_pk_fma_f32 v[114:115], v[122:123], v[110:111], v[114:115] op_sel_hi:[1,0,1]
	v_pk_fma_f32 v[118:119], v[118:119], v[110:111], v[126:127] op_sel_hi:[1,0,1]
	v_pk_mul_f32 v[122:123], v[110:111], v[120:121] op_sel_hi:[0,1]
	v_pk_mul_f32 v[110:111], v[110:111], v[116:117] op_sel_hi:[0,1]
	v_pk_fma_f32 v[120:121], v[148:149], v[138:139], v[110:111] op_sel_hi:[0,1,1]
	v_lshl_add_u64 v[110:111], s[16:17], 0, v[104:105]
	v_pk_fma_f32 v[126:127], v[148:149], v[136:137], v[122:123] op_sel_hi:[0,1,1]
	v_cvt_pk_bf16_f32 v136, v128, v129
	v_cvt_pk_bf16_f32 v138, v118, v119
	v_cvt_pk_bf16_f32 v137, v124, v125
	v_cvt_pk_bf16_f32 v139, v114, v115
	v_add_co_u32_e32 v116, vcc, 0x9008000, v110
	v_permlane16_swap_b32_e32 v136, v138
	v_permlane16_swap_b32_e32 v137, v139
	v_addc_co_u32_e32 v117, vcc, 0, v111, vcc
	ds_write_b128 v247, v[136:139] offset:0
	s_waitcnt lgkmcnt(0)
	s_barrier
	s_add_i32 s22, s29, 9
	s_cmp_gt_u32 s22, 56
	s_cbranch_scc1 .LBB0_1227
	v_add_co_u32_e32 v6, vcc, 0xd020000, v112
	s_nop 1
	v_addc_co_u32_e32 v7, vcc, 0, v113, vcc
	global_load_dwordx4 v[2:5], v[6:7], off
	s_nop 0
	global_load_dwordx4 v[6:9], v[6:7], off offset:64
	s_and_saveexec_b64 s[22:23], s[8:9]
	s_cbranch_execz .LBB0_1226
	v_lshl_add_u64 v[10:11], s[16:17], 0, v[106:107]
	v_add_co_u32_e32 v10, vcc, 0xe020000, v10
	s_nop 1
	v_addc_co_u32_e32 v11, vcc, 0, v11, vcc
	global_load_dwordx4 v[10:13], v[10:11], off

.LBB0_1229:
	s_or_b64 exec, exec, s[22:23]
	ds_read_b128 v[240:243], v246 offset:0
	v_lshl_add_u64 v[244:245], v[116:117], 0, v[248:249]
	s_waitcnt lgkmcnt(0)
	global_store_dwordx4 v[244:245], v[240:243], off offset:256
	s_and_saveexec_b64 s[98:99], s[10:11]
	s_cbranch_execz .LBB0_1221
	v_lshl_add_u64 v[122:123], s[16:17], 0, v[102:103]
	v_add_co_u32_e32 v122, vcc, 0x9010000, v122
	v_cvt_pk_bf16_f32 v116, v126, v127
	v_cvt_pk_bf16_f32 v117, v120, v121
	v_addc_co_u32_e32 v123, vcc, 0, v123, vcc
	global_store_dwordx2 v[122:123], v[116:117], off offset:256

.LBB0_1223:
	s_or_b64 exec, exec, s[98:99]
	v_mov_b32_e32 v116, s28
	ds_read_b128 v[136:139], v133 offset:4608
	ds_read_b64 v[116:117], v116 offset:8
	ds_read_b128 v[140:143], v133 offset:4672
	ds_read_b128 v[144:147], v133 offset:6912
	s_waitcnt vmcnt(17) lgkmcnt(3)
	v_mfma_f32_16x16x32_bf16 v[136:139], v[14:17], v[136:139], 0
	s_waitcnt lgkmcnt(2)
	v_add_f32_e32 v116, v134, v116
	v_max_f32_e32 v117, v117, v117
	v_max_f32_e32 v134, v116, v117
	v_sub_f32_e32 v116, v116, v134
	v_mul_f32_e32 v116, 0x3fb8aa3b, v116
	v_exp_f32_e32 v148, v116
	v_mul_f32_e32 v116, 0xbfb8aa3b, v134
	s_waitcnt vmcnt(16) lgkmcnt(1)
	v_mfma_f32_16x16x32_bf16 v[136:139], v[18:21], v[140:143], v[136:139]
	v_exp_f32_e32 v150, v116
	ds_read_b128 v[140:143], v133 offset:6976
	v_pk_mul_f32 v[116:117], v[128:129], v[148:149] op_sel_hi:[1,0]
	s_waitcnt lgkmcnt(1)
	v_mfma_f32_16x16x32_bf16 v[144:147], v[14:17], v[144:147], 0
	v_mul_f32_e64 v122, v124, v148
	v_mul_f32_e64 v123, v125, v148
	s_nop 0
	v_pk_fma_f32 v[128:129], v[136:137], v[150:151], v[116:117] op_sel_hi:[1,0,1]
	v_pk_fma_f32 v[124:125], v[138:139], v[150:151], v[122:123] op_sel_hi:[1,0,1]
	v_mfma_f32_16x16x32_bf16 v[136:139], v[14:17], v[86:89], 0
	s_waitcnt lgkmcnt(0)
	v_mfma_f32_16x16x32_bf16 v[140:143], v[18:21], v[140:143], v[144:147]
	v_mfma_f32_16x16x32_bf16 v[136:139], v[18:21], v[86:89], v[136:139]
	s_nop 6
	v_mul_f32_e64 v116, v150, v142
	v_mul_f32_e64 v117, v150, v143
	v_pk_mul_f32 v[122:123], v[150:151], v[140:141] op_sel_hi:[0,1]
	v_pk_fma_f32 v[116:117], v[114:115], v[148:149], v[116:117] op_sel_hi:[1,0,1]
	v_pk_fma_f32 v[122:123], v[118:119], v[148:149], v[122:123] op_sel_hi:[1,0,1]
	v_pk_mul_f32 v[114:115], v[150:151], v[138:139] op_sel_hi:[0,1]
	v_pk_mul_f32 v[118:119], v[150:151], v[136:137] op_sel_hi:[0,1]
	v_pk_fma_f32 v[114:115], v[120:121], v[148:149], v[114:115] op_sel_hi:[1,0,1]
	v_cvt_pk_bf16_f32 v136, v128, v129
	v_cvt_pk_bf16_f32 v138, v122, v123
	v_cvt_pk_bf16_f32 v137, v124, v125
	v_cvt_pk_bf16_f32 v139, v116, v117
	v_add_co_u32_e32 v120, vcc, 0x9010000, v110
	v_pk_fma_f32 v[118:119], v[126:127], v[148:149], v[118:119] op_sel_hi:[1,0,1]
	v_permlane16_swap_b32_e32 v136, v138
	v_permlane16_swap_b32_e32 v137, v139
	v_addc_co_u32_e32 v121, vcc, 0, v111, vcc
	ds_write_b128 v247, v[136:139] offset:8704
	s_waitcnt lgkmcnt(0)
	s_barrier
	s_add_i32 s22, s29, 10
	s_cmp_gt_u32 s22, 56
	s_cbranch_scc1 .LBB0_1237
	v_add_co_u32_e32 v18, vcc, 0xd024000, v112
	s_nop 1
	v_addc_co_u32_e32 v19, vcc, 0, v113, vcc
	global_load_dwordx4 v[14:17], v[18:19], off
	s_nop 0
	global_load_dwordx4 v[18:21], v[18:19], off offset:64
	s_and_saveexec_b64 s[22:23], s[8:9]
	s_cbranch_execz .LBB0_1236
	v_lshl_add_u64 v[22:23], s[16:17], 0, v[106:107]
	v_add_co_u32_e32 v22, vcc, 0xe024000, v22
	s_nop 1
	v_addc_co_u32_e32 v23, vcc, 0, v23, vcc
	global_load_dwordx4 v[22:25], v[22:23], off

.LBB0_1239:
	s_or_b64 exec, exec, s[22:23]
	ds_read_b128 v[240:243], v246 offset:8704
	v_lshl_add_u64 v[244:245], v[120:121], 0, v[248:249]
	s_waitcnt lgkmcnt(0)
	global_store_dwordx4 v[244:245], v[240:243], off offset:512
	s_and_saveexec_b64 s[98:99], s[10:11]
	s_cbranch_execz .LBB0_1231
	v_lshl_add_u64 v[126:127], s[16:17], 0, v[102:103]
	v_add_co_u32_e32 v126, vcc, 0x9018000, v126
	v_cvt_pk_bf16_f32 v120, v118, v119
	v_cvt_pk_bf16_f32 v121, v114, v115
	v_addc_co_u32_e32 v127, vcc, 0, v127, vcc
	global_store_dwordx2 v[126:127], v[120:121], off offset:512

.LBB0_1233:
	s_or_b64 exec, exec, s[98:99]
	v_mov_b32_e32 v120, s28
	ds_read_b128 v[136:139], v133 offset:9216
	ds_read_b64 v[120:121], v120 offset:16
	ds_read_b128 v[140:143], v133 offset:9280
	ds_read_b128 v[144:147], v133 offset:11520
	s_waitcnt vmcnt(18) lgkmcnt(3)
	v_mfma_f32_16x16x32_bf16 v[136:139], v[26:29], v[136:139], 0
	s_waitcnt lgkmcnt(2)
	v_add_f32_e32 v120, v134, v120
	v_max_f32_e32 v121, v121, v121
	v_max_f32_e32 v134, v120, v121
	v_sub_f32_e32 v120, v120, v134
	v_mul_f32_e32 v120, 0x3fb8aa3b, v120
	v_exp_f32_e32 v148, v120
	v_mul_f32_e32 v120, 0xbfb8aa3b, v134
	s_waitcnt vmcnt(17) lgkmcnt(1)
	v_mfma_f32_16x16x32_bf16 v[136:139], v[30:33], v[140:143], v[136:139]
	v_exp_f32_e32 v150, v120
	ds_read_b128 v[140:143], v133 offset:11584
	v_pk_mul_f32 v[120:121], v[128:129], v[148:149] op_sel_hi:[1,0]
	s_waitcnt lgkmcnt(1)
	v_mfma_f32_16x16x32_bf16 v[144:147], v[26:29], v[144:147], 0
	v_mul_f32_e64 v124, v124, v148
	v_mul_f32_e64 v125, v125, v148
	s_nop 0
	v_pk_fma_f32 v[126:127], v[136:137], v[150:151], v[120:121] op_sel_hi:[1,0,1]
	v_pk_fma_f32 v[124:125], v[138:139], v[150:151], v[124:125] op_sel_hi:[1,0,1]
	v_mfma_f32_16x16x32_bf16 v[136:139], v[26:29], v[86:89], 0
	s_waitcnt lgkmcnt(0)
	v_mfma_f32_16x16x32_bf16 v[140:143], v[30:33], v[140:143], v[144:147]
	v_mfma_f32_16x16x32_bf16 v[136:139], v[30:33], v[86:89], v[136:139]
	s_nop 6
	v_mul_f32_e64 v120, v150, v142
	v_mul_f32_e64 v121, v150, v143
	v_pk_mul_f32 v[128:129], v[150:151], v[140:141] op_sel_hi:[0,1]
	v_pk_fma_f32 v[116:117], v[116:117], v[148:149], v[120:121] op_sel_hi:[1,0,1]
	v_pk_fma_f32 v[120:121], v[122:123], v[148:149], v[128:129] op_sel_hi:[1,0,1]
	v_pk_mul_f32 v[122:123], v[150:151], v[138:139] op_sel_hi:[0,1]
	v_pk_mul_f32 v[128:129], v[150:151], v[136:137] op_sel_hi:[0,1]
	v_pk_fma_f32 v[114:115], v[114:115], v[148:149], v[122:123] op_sel_hi:[1,0,1]
	v_cvt_pk_bf16_f32 v136, v126, v127
	v_cvt_pk_bf16_f32 v138, v120, v121
	v_cvt_pk_bf16_f32 v137, v124, v125
	v_cvt_pk_bf16_f32 v139, v116, v117
	v_add_co_u32_e32 v122, vcc, 0x9018000, v110
	v_pk_fma_f32 v[118:119], v[118:119], v[148:149], v[128:129] op_sel_hi:[1,0,1]
	v_permlane16_swap_b32_e32 v136, v138
	v_permlane16_swap_b32_e32 v137, v139
	v_addc_co_u32_e32 v123, vcc, 0, v111, vcc
	ds_write_b128 v247, v[136:139] offset:0
	s_waitcnt lgkmcnt(0)
	s_barrier
	s_add_i32 s22, s29, 11
	s_cmp_gt_u32 s22, 56
	s_cbranch_scc1 .LBB0_1247
	v_add_co_u32_e32 v30, vcc, 0xd028000, v112
	s_nop 1
	v_addc_co_u32_e32 v31, vcc, 0, v113, vcc
	global_load_dwordx4 v[26:29], v[30:31], off
	s_nop 0
	global_load_dwordx4 v[30:33], v[30:31], off offset:64
	s_and_saveexec_b64 s[22:23], s[8:9]
	s_cbranch_execz .LBB0_1246
	v_lshl_add_u64 v[34:35], s[16:17], 0, v[106:107]
	v_add_co_u32_e32 v34, vcc, 0xe028000, v34
	s_nop 1
	v_addc_co_u32_e32 v35, vcc, 0, v35, vcc
	global_load_dwordx4 v[34:37], v[34:35], off

.LBB0_1249:
	s_or_b64 exec, exec, s[22:23]
	ds_read_b128 v[240:243], v246 offset:0
	v_lshl_add_u64 v[244:245], v[122:123], 0, v[248:249]
	s_waitcnt lgkmcnt(0)
	global_store_dwordx4 v[244:245], v[240:243], off offset:768
	s_and_saveexec_b64 s[98:99], s[10:11]
	s_cbranch_execz .LBB0_1241
	v_lshl_add_u64 v[128:129], s[16:17], 0, v[102:103]
	v_add_co_u32_e32 v128, vcc, 0x9020000, v128
	v_cvt_pk_bf16_f32 v122, v118, v119
	v_cvt_pk_bf16_f32 v123, v114, v115
	v_addc_co_u32_e32 v129, vcc, 0, v129, vcc
	global_store_dwordx2 v[128:129], v[122:123], off offset:768

.LBB0_1243:
	s_or_b64 exec, exec, s[98:99]
	v_mov_b32_e32 v122, s28
	ds_read_b128 v[136:139], v133 offset:13824
	ds_read_b64 v[122:123], v122 offset:24
	ds_read_b128 v[140:143], v133 offset:13888
	ds_read_b128 v[144:147], v133 offset:16128
	s_waitcnt vmcnt(19) lgkmcnt(3)
	v_mfma_f32_16x16x32_bf16 v[136:139], v[38:41], v[136:139], 0
	s_waitcnt lgkmcnt(2)
	v_add_f32_e32 v122, v134, v122
	v_max_f32_e32 v123, v123, v123
	v_max_f32_e32 v128, v122, v123
	v_sub_f32_e32 v122, v122, v128
	v_mul_f32_e32 v122, 0x3fb8aa3b, v122
	v_exp_f32_e32 v148, v122
	v_mul_f32_e32 v122, 0xbfb8aa3b, v128
	s_waitcnt vmcnt(18) lgkmcnt(1)
	v_mfma_f32_16x16x32_bf16 v[134:137], v[42:45], v[140:143], v[136:139]
	v_mul_f32_e64 v126, v126, v148
	v_mul_f32_e64 v127, v127, v148
	s_nop 0
	ds_read_b128 v[138:141], v133 offset:16192
	s_waitcnt lgkmcnt(1)
	v_mfma_f32_16x16x32_bf16 v[142:145], v[38:41], v[144:147], 0
	v_exp_f32_e32 v146, v122
	v_pk_mul_f32 v[122:123], v[124:125], v[148:149] op_sel_hi:[1,0]
	v_pk_fma_f32 v[124:125], v[134:135], v[146:147], v[126:127] op_sel_hi:[1,0,1]
	v_pk_fma_f32 v[122:123], v[136:137], v[146:147], v[122:123] op_sel_hi:[1,0,1]
	v_mfma_f32_16x16x32_bf16 v[134:137], v[38:41], v[86:89], 0
	s_waitcnt lgkmcnt(0)
	v_mfma_f32_16x16x32_bf16 v[138:141], v[42:45], v[138:141], v[142:145]
	v_mfma_f32_16x16x32_bf16 v[134:137], v[42:45], v[86:89], v[134:137]
	s_nop 6
	v_mul_f32_e64 v126, v146, v140
	v_mul_f32_e64 v127, v146, v141
	v_pk_mul_f32 v[138:139], v[146:147], v[138:139] op_sel_hi:[0,1]
	v_pk_fma_f32 v[116:117], v[116:117], v[148:149], v[126:127] op_sel_hi:[1,0,1]
	v_pk_fma_f32 v[120:121], v[120:121], v[148:149], v[138:139] op_sel_hi:[1,0,1]
	v_pk_mul_f32 v[126:127], v[146:147], v[136:137] op_sel_hi:[0,1]
	v_pk_mul_f32 v[134:135], v[146:147], v[134:135] op_sel_hi:[0,1]
	v_pk_fma_f32 v[114:115], v[114:115], v[148:149], v[126:127] op_sel_hi:[1,0,1]
	v_pk_fma_f32 v[118:119], v[118:119], v[148:149], v[134:135] op_sel_hi:[1,0,1]
	v_cvt_pk_bf16_f32 v134, v124, v125
	v_cvt_pk_bf16_f32 v136, v120, v121
	v_cvt_pk_bf16_f32 v135, v122, v123
	v_cvt_pk_bf16_f32 v137, v116, v117
	v_add_co_u32_e32 v126, vcc, 0x9020000, v110
	v_permlane16_swap_b32_e32 v134, v136
	v_permlane16_swap_b32_e32 v135, v137
	v_addc_co_u32_e32 v127, vcc, 0, v111, vcc
	ds_write_b128 v247, v[134:137] offset:8704
	s_waitcnt lgkmcnt(0)
	s_barrier
	s_add_i32 s22, s29, 12
	s_cmp_gt_u32 s22, 56
	s_cbranch_scc1 .LBB0_1257
	v_add_co_u32_e32 v42, vcc, 0xd02c000, v112
	s_nop 1
	v_addc_co_u32_e32 v43, vcc, 0, v113, vcc
	global_load_dwordx4 v[38:41], v[42:43], off
	s_nop 0
	global_load_dwordx4 v[42:45], v[42:43], off offset:64
	s_and_saveexec_b64 s[22:23], s[8:9]
	s_cbranch_execz .LBB0_1256
	v_lshl_add_u64 v[46:47], s[16:17], 0, v[106:107]
	v_add_co_u32_e32 v46, vcc, 0xe02c000, v46
	s_nop 1
	v_addc_co_u32_e32 v47, vcc, 0, v47, vcc
	global_load_dwordx4 v[46:49], v[46:47], off

.LBB0_1259:
	s_or_b64 exec, exec, s[22:23]
	ds_read_b128 v[240:243], v246 offset:8704
	v_lshl_add_u64 v[244:245], v[126:127], 0, v[248:249]
	s_waitcnt lgkmcnt(0)
	global_store_dwordx4 v[244:245], v[240:243], off offset:1024
	s_and_saveexec_b64 s[98:99], s[10:11]
	s_cbranch_execz .LBB0_1251
	v_lshl_add_u64 v[134:135], s[16:17], 0, v[102:103]
	v_add_co_u32_e32 v134, vcc, 0x9028000, v134
	v_cvt_pk_bf16_f32 v126, v118, v119
	v_cvt_pk_bf16_f32 v127, v114, v115
	v_addc_co_u32_e32 v135, vcc, 0, v135, vcc
	global_store_dwordx2 v[134:135], v[126:127], off offset:1024

.LBB0_1253:
	s_or_b64 exec, exec, s[98:99]
	v_mov_b32_e32 v126, s28
	ds_read_b128 v[134:137], v133 offset:18432
	ds_read_b64 v[126:127], v126 offset:32
	ds_read_b128 v[138:141], v133 offset:18496
	ds_read_b128 v[142:145], v133 offset:20736
	s_waitcnt vmcnt(20) lgkmcnt(3)
	v_mfma_f32_16x16x32_bf16 v[134:137], v[50:53], v[134:137], 0
	s_waitcnt lgkmcnt(2)
	v_add_f32_e32 v128, v128, v126
	v_max_f32_e32 v126, v127, v127
	v_max_f32_e32 v126, v128, v126
	v_sub_f32_e32 v127, v128, v126
	v_mul_f32_e32 v127, 0x3fb8aa3b, v127
	v_exp_f32_e32 v128, v127
	v_mul_f32_e32 v127, 0xbfb8aa3b, v126
	s_waitcnt vmcnt(19) lgkmcnt(1)
	v_mfma_f32_16x16x32_bf16 v[134:137], v[54:57], v[138:141], v[134:137]
	v_exp_f32_e32 v146, v127
	ds_read_b128 v[138:141], v133 offset:20800
	v_pk_mul_f32 v[124:125], v[124:125], v[128:129] op_sel_hi:[1,0]
	s_waitcnt lgkmcnt(1)
	v_mfma_f32_16x16x32_bf16 v[142:145], v[50:53], v[142:145], 0
	v_mul_f32_e64 v122, v122, v128
	v_mul_f32_e64 v123, v123, v128
	s_nop 0
	v_pk_fma_f32 v[124:125], v[134:135], v[146:147], v[124:125] op_sel_hi:[1,0,1]
	v_pk_fma_f32 v[122:123], v[136:137], v[146:147], v[122:123] op_sel_hi:[1,0,1]
	v_mfma_f32_16x16x32_bf16 v[134:137], v[50:53], v[86:89], 0
	s_waitcnt lgkmcnt(0)
	v_mfma_f32_16x16x32_bf16 v[138:141], v[54:57], v[138:141], v[142:145]
	v_mfma_f32_16x16x32_bf16 v[134:137], v[54:57], v[86:89], v[134:137]
	s_nop 6
	v_mul_f32_e64 v140, v146, v140
	v_mul_f32_e64 v141, v146, v141
	v_pk_mul_f32 v[138:139], v[146:147], v[138:139] op_sel_hi:[0,1]
	v_pk_fma_f32 v[116:117], v[116:117], v[128:129], v[140:141] op_sel_hi:[1,0,1]
	v_pk_fma_f32 v[120:121], v[120:121], v[128:129], v[138:139] op_sel_hi:[1,0,1]
	v_pk_mul_f32 v[136:137], v[146:147], v[136:137] op_sel_hi:[0,1]
	v_pk_mul_f32 v[134:135], v[146:147], v[134:135] op_sel_hi:[0,1]
	v_pk_fma_f32 v[114:115], v[114:115], v[128:129], v[136:137] op_sel_hi:[1,0,1]
	v_pk_fma_f32 v[118:119], v[118:119], v[128:129], v[134:135] op_sel_hi:[1,0,1]
	v_cvt_pk_bf16_f32 v134, v124, v125
	v_cvt_pk_bf16_f32 v136, v120, v121
	v_cvt_pk_bf16_f32 v135, v122, v123
	v_cvt_pk_bf16_f32 v137, v116, v117
	v_add_co_u32_e32 v128, vcc, 0x9028000, v110
	v_permlane16_swap_b32_e32 v134, v136
	v_permlane16_swap_b32_e32 v135, v137
	v_addc_co_u32_e32 v129, vcc, 0, v111, vcc
	ds_write_b128 v247, v[134:137] offset:0
	s_waitcnt lgkmcnt(0)
	s_barrier
	s_add_i32 s22, s29, 13
	s_cmp_gt_u32 s22, 56
	s_cbranch_scc1 .LBB0_1267
	v_add_co_u32_e32 v54, vcc, 0xd030000, v112
	s_nop 1
	v_addc_co_u32_e32 v55, vcc, 0, v113, vcc
	global_load_dwordx4 v[50:53], v[54:55], off
	s_nop 0
	global_load_dwordx4 v[54:57], v[54:55], off offset:64
	s_and_saveexec_b64 s[22:23], s[8:9]
	s_cbranch_execz .LBB0_1266
	v_lshl_add_u64 v[58:59], s[16:17], 0, v[106:107]
	v_add_co_u32_e32 v58, vcc, 0xe030000, v58
	s_nop 1
	v_addc_co_u32_e32 v59, vcc, 0, v59, vcc
	global_load_dwordx4 v[58:61], v[58:59], off

.LBB0_1269:
	s_or_b64 exec, exec, s[22:23]
	ds_read_b128 v[240:243], v246 offset:0
	v_lshl_add_u64 v[244:245], v[128:129], 0, v[248:249]
	s_waitcnt lgkmcnt(0)
	global_store_dwordx4 v[244:245], v[240:243], off offset:1280
	s_and_saveexec_b64 s[98:99], s[10:11]
	s_cbranch_execz .LBB0_1261
	v_lshl_add_u64 v[134:135], s[16:17], 0, v[102:103]
	v_add_co_u32_e32 v134, vcc, 0x9030000, v134
	v_cvt_pk_bf16_f32 v128, v118, v119
	v_cvt_pk_bf16_f32 v129, v114, v115
	v_addc_co_u32_e32 v135, vcc, 0, v135, vcc
	global_store_dwordx2 v[134:135], v[128:129], off offset:1280

.LBB0_1263:
	s_or_b64 exec, exec, s[98:99]
	v_mov_b32_e32 v127, s28
	ds_read_b128 v[134:137], v133 offset:23040
	ds_read_b64 v[128:129], v127 offset:40
	ds_read_b128 v[138:141], v133 offset:23104
	ds_read_b128 v[142:145], v133 offset:25344
	s_waitcnt vmcnt(21) lgkmcnt(3)
	v_mfma_f32_16x16x32_bf16 v[134:137], v[62:65], v[134:137], 0
	s_waitcnt lgkmcnt(2)
	v_add_f32_e32 v126, v126, v128
	v_max_f32_e32 v127, v129, v129
	v_max_f32_e32 v128, v126, v127
	v_sub_f32_e32 v126, v126, v128
	v_mul_f32_e32 v126, 0x3fb8aa3b, v126
	v_exp_f32_e32 v146, v126
	v_mul_f32_e32 v126, 0xbfb8aa3b, v128
	s_waitcnt vmcnt(20) lgkmcnt(1)
	v_mfma_f32_16x16x32_bf16 v[134:137], v[66:69], v[138:141], v[134:137]
	v_exp_f32_e32 v148, v126
	ds_read_b128 v[138:141], v133 offset:25408
	v_pk_mul_f32 v[124:125], v[124:125], v[146:147] op_sel_hi:[1,0]
	s_waitcnt lgkmcnt(1)
	v_mfma_f32_16x16x32_bf16 v[142:145], v[62:65], v[142:145], 0
	v_mul_f32_e64 v122, v122, v146
	v_mul_f32_e64 v123, v123, v146
	s_nop 0
	v_pk_fma_f32 v[126:127], v[134:135], v[148:149], v[124:125] op_sel_hi:[1,0,1]
	v_pk_fma_f32 v[122:123], v[136:137], v[148:149], v[122:123] op_sel_hi:[1,0,1]
	v_mfma_f32_16x16x32_bf16 v[134:137], v[62:65], v[86:89], 0
	s_waitcnt lgkmcnt(0)
	v_mfma_f32_16x16x32_bf16 v[138:141], v[66:69], v[138:141], v[142:145]
	v_mfma_f32_16x16x32_bf16 v[134:137], v[66:69], v[86:89], v[134:137]
	s_nop 6
	v_mul_f32_e64 v124, v148, v140
	v_mul_f32_e64 v125, v148, v141
	v_pk_mul_f32 v[138:139], v[148:149], v[138:139] op_sel_hi:[0,1]
	v_pk_fma_f32 v[116:117], v[116:117], v[146:147], v[124:125] op_sel_hi:[1,0,1]
	v_pk_fma_f32 v[124:125], v[120:121], v[146:147], v[138:139] op_sel_hi:[1,0,1]
	v_pk_mul_f32 v[120:121], v[148:149], v[136:137] op_sel_hi:[0,1]
	v_pk_mul_f32 v[134:135], v[148:149], v[134:135] op_sel_hi:[0,1]
	v_pk_fma_f32 v[114:115], v[114:115], v[146:147], v[120:121] op_sel_hi:[1,0,1]
	v_pk_fma_f32 v[120:121], v[118:119], v[146:147], v[134:135] op_sel_hi:[1,0,1]
	v_cvt_pk_bf16_f32 v134, v126, v127
	v_cvt_pk_bf16_f32 v136, v124, v125
	v_cvt_pk_bf16_f32 v135, v122, v123
	v_cvt_pk_bf16_f32 v137, v116, v117
	v_add_co_u32_e32 v118, vcc, 0x9030000, v110
	v_permlane16_swap_b32_e32 v134, v136
	v_permlane16_swap_b32_e32 v135, v137
	v_addc_co_u32_e32 v119, vcc, 0, v111, vcc
	ds_write_b128 v247, v[134:137] offset:8704
	s_waitcnt lgkmcnt(0)
	s_barrier
	s_add_i32 s22, s29, 14
	s_cmp_gt_u32 s22, 56
	s_cbranch_scc1 .LBB0_1277
	v_add_co_u32_e32 v66, vcc, 0xd034000, v112
	s_nop 1
	v_addc_co_u32_e32 v67, vcc, 0, v113, vcc
	global_load_dwordx4 v[62:65], v[66:67], off
	s_nop 0
	global_load_dwordx4 v[66:69], v[66:67], off offset:64
	s_and_saveexec_b64 s[22:23], s[8:9]
	s_cbranch_execz .LBB0_1276
	v_lshl_add_u64 v[70:71], s[16:17], 0, v[106:107]
	v_add_co_u32_e32 v70, vcc, 0xe034000, v70
	s_nop 1
	v_addc_co_u32_e32 v71, vcc, 0, v71, vcc
	global_load_dwordx4 v[70:73], v[70:71], off

.LBB0_1279:
	s_or_b64 exec, exec, s[22:23]
	ds_read_b128 v[240:243], v246 offset:8704
	v_lshl_add_u64 v[244:245], v[118:119], 0, v[248:249]
	s_waitcnt lgkmcnt(0)
	global_store_dwordx4 v[244:245], v[240:243], off offset:1536
	s_and_saveexec_b64 s[98:99], s[10:11]
	s_cbranch_execz .LBB0_1271
	v_lshl_add_u64 v[134:135], s[16:17], 0, v[102:103]
	v_add_co_u32_e32 v134, vcc, 0x9038000, v134
	v_cvt_pk_bf16_f32 v118, v120, v121
	v_cvt_pk_bf16_f32 v119, v114, v115
	v_addc_co_u32_e32 v135, vcc, 0, v135, vcc
	global_store_dwordx2 v[134:135], v[118:119], off offset:1536

.LBB0_1273:
	s_or_b64 exec, exec, s[98:99]
	v_mov_b32_e32 v118, s28
	ds_read_b128 v[134:137], v133 offset:27648
	ds_read_b64 v[118:119], v118 offset:48
	ds_read_b128 v[138:141], v133 offset:27712
	ds_read_b128 v[146:149], v133 offset:29952
	s_waitcnt vmcnt(22) lgkmcnt(3)
	v_mfma_f32_16x16x32_bf16 v[142:145], v[74:77], v[134:137], 0
	s_waitcnt lgkmcnt(2)
	v_add_f32_e32 v118, v128, v118
	v_max_f32_e32 v119, v119, v119
	v_max_f32_e32 v134, v118, v119
	v_sub_f32_e32 v118, v118, v134
	v_mul_f32_e32 v118, 0x3fb8aa3b, v118
	v_exp_f32_e32 v150, v118
	v_mul_f32_e32 v118, 0xbfb8aa3b, v134
	s_waitcnt vmcnt(21) lgkmcnt(1)
	v_mfma_f32_16x16x32_bf16 v[136:139], v[78:81], v[138:141], v[142:145]
	v_mul_f32_e64 v122, v122, v150
	v_mul_f32_e64 v123, v123, v150
	s_nop 0
	ds_read_b128 v[140:143], v133 offset:30016
	s_waitcnt lgkmcnt(1)
	v_mfma_f32_16x16x32_bf16 v[144:147], v[74:77], v[146:149], 0
	v_exp_f32_e32 v148, v118
	v_pk_mul_f32 v[118:119], v[126:127], v[150:151] op_sel_hi:[1,0]
	v_pk_fma_f32 v[122:123], v[138:139], v[148:149], v[122:123] op_sel_hi:[1,0,1]
	v_pk_fma_f32 v[126:127], v[136:137], v[148:149], v[118:119] op_sel_hi:[1,0,1]
	v_mfma_f32_16x16x32_bf16 v[136:139], v[74:77], v[86:89], 0
	s_waitcnt lgkmcnt(0)
	v_mfma_f32_16x16x32_bf16 v[140:143], v[78:81], v[140:143], v[144:147]
	v_mfma_f32_16x16x32_bf16 v[136:139], v[78:81], v[86:89], v[136:139]
	s_nop 6
	v_mul_f32_e64 v118, v148, v142
	v_mul_f32_e64 v119, v148, v143
	v_pk_mul_f32 v[128:129], v[148:149], v[140:141] op_sel_hi:[0,1]
	v_pk_fma_f32 v[118:119], v[116:117], v[150:151], v[118:119] op_sel_hi:[1,0,1]
	v_pk_fma_f32 v[128:129], v[124:125], v[150:151], v[128:129] op_sel_hi:[1,0,1]
	v_pk_mul_f32 v[116:117], v[148:149], v[138:139] op_sel_hi:[0,1]
	v_pk_mul_f32 v[124:125], v[148:149], v[136:137] op_sel_hi:[0,1]
	v_pk_fma_f32 v[116:117], v[114:115], v[150:151], v[116:117] op_sel_hi:[1,0,1]
	v_cvt_pk_bf16_f32 v136, v126, v127
	v_cvt_pk_bf16_f32 v138, v128, v129
	v_cvt_pk_bf16_f32 v137, v122, v123
	v_cvt_pk_bf16_f32 v139, v118, v119
	v_add_co_u32_e32 v114, vcc, 0x9038000, v110
	v_pk_fma_f32 v[120:121], v[120:121], v[150:151], v[124:125] op_sel_hi:[1,0,1]
	v_permlane16_swap_b32_e32 v136, v138
	v_permlane16_swap_b32_e32 v137, v139
	v_addc_co_u32_e32 v115, vcc, 0, v111, vcc
	ds_write_b128 v247, v[136:139] offset:0
	s_waitcnt lgkmcnt(0)
	s_barrier
	s_add_i32 s24, s29, 15
	s_cmp_gt_u32 s24, 56
	s_cbranch_scc1 .LBB0_1287
	v_add_co_u32_e32 v78, vcc, 0xd038000, v112
	s_nop 1
	v_addc_co_u32_e32 v79, vcc, 0, v113, vcc
	global_load_dwordx4 v[74:77], v[78:79], off
	s_nop 0
	global_load_dwordx4 v[78:81], v[78:79], off offset:64
	s_and_saveexec_b64 s[22:23], s[8:9]
	s_cbranch_execz .LBB0_1286
	v_lshl_add_u64 v[82:83], s[16:17], 0, v[106:107]
	v_add_co_u32_e32 v82, vcc, 0xe038000, v82
	s_nop 1
	v_addc_co_u32_e32 v83, vcc, 0, v83, vcc
	global_load_dwordx4 v[82:85], v[82:83], off

.LBB0_1289:
	s_or_b64 exec, exec, s[24:25]
	ds_read_b128 v[240:243], v246 offset:0
	v_lshl_add_u64 v[244:245], v[114:115], 0, v[248:249]
	s_waitcnt lgkmcnt(0)
	global_store_dwordx4 v[244:245], v[240:243], off offset:1792
	s_and_saveexec_b64 s[98:99], s[10:11]
	s_cbranch_execz .LBB0_1281
	v_lshl_add_u64 v[124:125], s[16:17], 0, v[102:103]
	v_add_co_u32_e32 v124, vcc, 0x9040000, v124
	v_cvt_pk_bf16_f32 v114, v120, v121
	v_cvt_pk_bf16_f32 v115, v116, v117
	v_addc_co_u32_e32 v125, vcc, 0, v125, vcc
	global_store_dwordx2 v[124:125], v[114:115], off offset:1792
